# layer-1 w_in transpose tiles: next tile loads issued before this tile's stores (double buffer)
# baseline (speedup 1.0000x reference)
.LBB0_86:
	s_or_b64 exec, exec, s[0:1]
	v_readlane_b32 s22, v250, 19
	v_readlane_b32 s23, v250, 20
	s_xor_b64 s[0:1], s[22:23], -1
	v_readlane_b32 s14, v252, 51
	v_readlane_b32 s15, v252, 52
	v_writelane_b32 v250, s0, 23
	s_andn2_b64 vcc, exec, s[0:1]
	s_nop 0
	v_writelane_b32 v250, s1, 24
	s_cbranch_vccnz .LBB0_89
	v_readlane_b32 s0, v252, 33
	v_readlane_b32 s1, v252, 34
	s_andn2_b64 vcc, exec, s[0:1]
	v_readlane_b32 s4, v251, 51
	s_mov_b32 s5, s92
	s_barrier
	s_cbranch_vccnz .LBB0_89
	v_lshrrev_b32_e32 v133, 6, v1
	v_mul_u32_u24_e32 v133, 0xf000, v133
	v_and_b32_e32 v134, 63, v1
	v_lshl_add_u32 v132, v134, 4, v133
	s_cmp_lt_i32 s5, 0x780
	s_cbranch_scc0 .Ltr1_nopf_a
	s_mul_hi_i32 s98, s5, 0x88888889
	s_add_i32 s98, s98, s5
	s_lshr_b32 s99, s98, 31
	s_ashr_i32 s98, s98, 5
	s_add_i32 s98, s98, s99
	s_mul_i32 s99, s98, 60
	s_sub_i32 s99, s5, s99
	s_lshl_b32 s99, s99, 10
	s_mul_i32 s98, s98, 0x3c0000
	s_add_i32 s99, s99, s98
	s_add_u32 s100, s17, s99
	s_addc_u32 s101, s20, 0
	global_load_dwordx4 v[100:103], v132, s[100:101]
	s_add_u32 s100, s100, 0x78000
	s_addc_u32 s101, s101, 0
	global_load_dwordx4 v[104:107], v132, s[100:101]
	s_add_u32 s100, s100, 0x78000
	s_addc_u32 s101, s101, 0
	global_load_dwordx4 v[108:111], v132, s[100:101]
	s_add_u32 s100, s100, 0x78000
	s_addc_u32 s101, s101, 0
	global_load_dwordx4 v[112:115], v132, s[100:101]
	s_add_u32 s100, s100, 0x78000
	s_addc_u32 s101, s101, 0
	global_load_dwordx4 v[116:119], v132, s[100:101]
	s_add_u32 s100, s100, 0x78000
	s_addc_u32 s101, s101, 0
	global_load_dwordx4 v[120:123], v132, s[100:101]
	s_add_u32 s100, s100, 0x78000
	s_addc_u32 s101, s101, 0
	global_load_dwordx4 v[124:127], v132, s[100:101]
	s_add_u32 s100, s100, 0x78000
	s_addc_u32 s101, s101, 0
	global_load_dwordx4 v[128:131], v132, s[100:101]

.LBB0_88:
	s_mul_hi_i32 s0, s5, 0x88888889
	s_add_i32 s0, s0, s5
	s_lshr_b32 s1, s0, 31
	s_ashr_i32 s6, s0, 5
	s_add_i32 s6, s6, s1
	s_mul_i32 s1, s6, 0xffffc400
	s_add_i32 s8, s4, s1
	s_ashr_i32 s9, s8, 31
	s_lshl_b32 s0, s6, 6
	v_mov_b32_e32 v7, v1
	s_lshl_b64 s[8:9], s[8:9], 2
	s_add_u32 s8, s17, s8
	v_lshlrev_b32_e32 v2, 4, v7
	v_add_u32_e32 v24, 0x800, v7
	s_addc_u32 s9, s20, s9
	v_and_b32_e32 v194, 0x3f0, v2
	v_ashrrev_i32_e32 v40, 6, v7
	v_ashrrev_i32_e32 v44, 6, v24
	v_lshl_add_u64 v[2:3], s[8:9], 0, v[194:195]
	v_add_u32_e32 v4, s0, v40
	v_add_u32_e32 v41, 0x200, v7
	v_add_u32_e32 v24, s0, v44
	v_add_u32_e32 v28, 0xa00, v7
	v_mad_i64_i32 v[4:5], s[8:9], v4, s25, v[2:3]
	v_ashrrev_i32_e32 v42, 6, v41
	v_mad_i64_i32 v[24:25], s[8:9], v24, s25, v[2:3]
	v_ashrrev_i32_e32 v45, 6, v28
	v_add_u32_e32 v6, 0x400, v7
	v_add_u32_e32 v4, s0, v42
	v_add_u32_e32 v28, s0, v45
	v_add_u32_e32 v32, 0xc00, v7
	v_mad_i64_i32 v[4:5], s[8:9], v4, s25, v[2:3]
	v_ashrrev_i32_e32 v43, 6, v6
	v_mad_i64_i32 v[28:29], s[8:9], v28, s25, v[2:3]
	v_ashrrev_i32_e32 v46, 6, v32
	v_add_u32_e32 v32, s0, v46
	v_add_u32_e32 v4, s0, v43
	v_mad_i64_i32 v[4:5], s[8:9], v4, s25, v[2:3]
	v_mad_i64_i32 v[32:33], s[8:9], v32, s25, v[2:3]
	v_add_u32_e32 v36, 0xe00, v7
	v_add_u32_e32 v4, 0x600, v7
	v_ashrrev_i32_e32 v5, 6, v4
	v_ashrrev_i32_e32 v47, 6, v36
	v_add_u32_e32 v20, s0, v5
	v_add_u32_e32 v36, s0, v47
	v_mad_i64_i32 v[20:21], s[8:9], v20, s25, v[2:3]
	v_mad_i64_i32 v[2:3], s[8:9], v36, s25, v[2:3]
	v_lshlrev_b32_e32 v48, 3, v7
	v_ashrrev_i32_e32 v7, 3, v7
	v_and_b32_e32 v2, 0x1f8, v48
	s_waitcnt vmcnt(4)
	v_mov_b32_e32 v8, v100
	v_mov_b32_e32 v9, v101
	v_mov_b32_e32 v10, v102
	v_mov_b32_e32 v11, v103
	v_mov_b32_e32 v12, v104
	v_mov_b32_e32 v13, v105
	v_mov_b32_e32 v14, v106
	v_mov_b32_e32 v15, v107
	v_mov_b32_e32 v16, v108
	v_mov_b32_e32 v17, v109
	v_mov_b32_e32 v18, v110
	v_mov_b32_e32 v19, v111
	v_mov_b32_e32 v20, v112
	v_mov_b32_e32 v21, v113
	v_mov_b32_e32 v22, v114
	v_mov_b32_e32 v23, v115
	v_mov_b32_e32 v24, v116
	v_mov_b32_e32 v25, v117
	v_mov_b32_e32 v26, v118
	v_mov_b32_e32 v27, v119
	v_mov_b32_e32 v28, v120
	v_mov_b32_e32 v29, v121
	v_mov_b32_e32 v30, v122
	v_mov_b32_e32 v31, v123
	v_mov_b32_e32 v32, v124
	v_mov_b32_e32 v33, v125
	v_mov_b32_e32 v34, v126
	v_mov_b32_e32 v35, v127
	v_mov_b32_e32 v36, v128
	v_mov_b32_e32 v37, v129
	v_mov_b32_e32 v38, v130
	v_mov_b32_e32 v39, v131
	v_cvt_pk_bf16_f32 v3, v8, v9
	s_ashr_i32 s1, s0, 31
	v_mad_u64_u32 v[8:9], s[8:9], v40, s33, v[2:3]
	ds_write_b32 v8, v3
	v_cvt_pk_bf16_f32 v3, v10, v11
	ds_write_b32 v8, v3 offset:4
	v_cvt_pk_bf16_f32 v3, v12, v13
	s_mulk_i32 s6, 0x3c00
	v_mad_u64_u32 v[8:9], s[8:9], v42, s33, v[2:3]
	ds_write_b32 v8, v3
	v_cvt_pk_bf16_f32 v3, v14, v15
	ds_write_b32 v8, v3 offset:4
	v_cvt_pk_bf16_f32 v3, v16, v17
	s_lshl_b64 s[0:1], s[0:1], 1
	v_mad_u64_u32 v[8:9], s[8:9], v43, s33, v[2:3]
	ds_write_b32 v8, v3
	v_cvt_pk_bf16_f32 v3, v18, v19
	ds_write_b32 v8, v3 offset:4
	v_cvt_pk_bf16_f32 v3, v20, v21
	s_add_u32 s0, s94, s0
	v_mad_u64_u32 v[8:9], s[8:9], v5, s33, v[2:3]
	ds_write_b32 v8, v3
	v_cvt_pk_bf16_f32 v3, v22, v23
	ds_write_b32 v8, v3 offset:4
	v_cvt_pk_bf16_f32 v3, v24, v25
	s_addc_u32 s1, s95, s1
	v_mad_u64_u32 v[8:9], s[8:9], v44, s33, v[2:3]
	ds_write_b32 v8, v3
	v_cvt_pk_bf16_f32 v3, v26, v27
	ds_write_b32 v8, v3 offset:4
	v_cvt_pk_bf16_f32 v3, v28, v29
	s_add_i32 s5, s5, s30
	v_mad_u64_u32 v[8:9], s[8:9], v45, s33, v[2:3]
	ds_write_b32 v8, v3
	v_cvt_pk_bf16_f32 v3, v30, v31
	ds_write_b32 v8, v3 offset:4
	v_cvt_pk_bf16_f32 v3, v32, v33
	s_nop 0
	v_mad_u64_u32 v[8:9], s[8:9], v46, s33, v[2:3]
	ds_write_b32 v8, v3
	v_cvt_pk_bf16_f32 v3, v34, v35
	ds_write_b32 v8, v3 offset:4
	v_cvt_pk_bf16_f32 v5, v36, v37
	v_mad_u64_u32 v[2:3], s[8:9], v47, s33, v[2:3]
	ds_write_b32 v2, v5
	v_and_b32_e32 v5, 56, v48
	v_lshlrev_b32_e32 v194, 1, v5
	v_mul_u32_u24_e32 v5, 0x204, v5
	v_lshl_add_u32 v8, v7, 1, v5
	v_cvt_pk_bf16_f32 v3, v38, v39
	ds_write_b32 v2, v3 offset:4
	s_waitcnt lgkmcnt(0)
	s_barrier
	s_cmp_lt_i32 s5, 0x780
	s_cbranch_scc0 .Ltr1_nopf_b
	s_mul_hi_i32 s98, s5, 0x88888889
	s_add_i32 s98, s98, s5
	s_lshr_b32 s99, s98, 31
	s_ashr_i32 s98, s98, 5
	s_add_i32 s98, s98, s99
	s_mul_i32 s99, s98, 60
	s_sub_i32 s99, s5, s99
	s_lshl_b32 s99, s99, 10
	s_mul_i32 s98, s98, 0x3c0000
	s_add_i32 s99, s99, s98
	s_add_u32 s100, s17, s99
	s_addc_u32 s101, s20, 0
	global_load_dwordx4 v[100:103], v132, s[100:101]
	s_add_u32 s100, s100, 0x78000
	s_addc_u32 s101, s101, 0
	global_load_dwordx4 v[104:107], v132, s[100:101]
	s_add_u32 s100, s100, 0x78000
	s_addc_u32 s101, s101, 0
	global_load_dwordx4 v[108:111], v132, s[100:101]
	s_add_u32 s100, s100, 0x78000
	s_addc_u32 s101, s101, 0
	global_load_dwordx4 v[112:115], v132, s[100:101]
	s_add_u32 s100, s100, 0x78000
	s_addc_u32 s101, s101, 0
	global_load_dwordx4 v[116:119], v132, s[100:101]
	s_add_u32 s100, s100, 0x78000
	s_addc_u32 s101, s101, 0
	global_load_dwordx4 v[120:123], v132, s[100:101]
	s_add_u32 s100, s100, 0x78000
	s_addc_u32 s101, s101, 0
	global_load_dwordx4 v[124:127], v132, s[100:101]
	s_add_u32 s100, s100, 0x78000
	s_addc_u32 s101, s101, 0
	global_load_dwordx4 v[128:131], v132, s[100:101]
.Ltr1_nopf_b:
	ds_read_u16 v12, v8
	ds_read_u16 v13, v8 offset:516
	ds_read_u16 v9, v8 offset:1032
	ds_read_u16 v14, v8 offset:1548
	ds_read_u16 v10, v8 offset:2064
	ds_read_u16 v15, v8 offset:2580
	ds_read_u16 v11, v8 offset:3096
	ds_read_u16 v8, v8 offset:3612
	v_subrev_u32_e32 v7, s6, v7
	v_lshl_add_u64 v[2:3], s[0:1], 0, v[194:195]
	s_waitcnt lgkmcnt(2)
	v_perm_b32 v10, v15, v10, s34
	v_perm_b32 v9, v14, v9, s34
	s_waitcnt lgkmcnt(0)
	v_perm_b32 v11, v8, v11, s34
	v_perm_b32 v8, v13, v12, s34
	v_add_u32_e32 v12, s4, v7
	v_ashrrev_i32_e32 v13, 31, v12
	v_lshlrev_b64 v[12:13], 12, v[12:13]
	v_lshl_add_u64 v[12:13], v[2:3], 0, v[12:13]
	v_ashrrev_i32_e32 v7, 3, v41
	global_store_dwordx4 v[12:13], v[8:11], off
	s_nop 1
	v_lshl_add_u32 v8, v7, 1, v5
	ds_read_u16 v12, v8
	ds_read_u16 v13, v8 offset:516
	ds_read_u16 v9, v8 offset:1032
	ds_read_u16 v14, v8 offset:1548
	ds_read_u16 v10, v8 offset:2064
	ds_read_u16 v15, v8 offset:2580
	ds_read_u16 v11, v8 offset:3096
	ds_read_u16 v8, v8 offset:3612
	v_subrev_u32_e32 v7, s6, v7
	s_waitcnt lgkmcnt(4)
	v_perm_b32 v9, v14, v9, s34
	s_waitcnt lgkmcnt(2)
	v_perm_b32 v10, v15, v10, s34
	s_waitcnt lgkmcnt(0)
	v_perm_b32 v11, v8, v11, s34
	v_perm_b32 v8, v13, v12, s34
	v_add_u32_e32 v12, s4, v7
	v_ashrrev_i32_e32 v13, 31, v12
	v_lshlrev_b64 v[12:13], 12, v[12:13]
	v_lshl_add_u64 v[12:13], v[2:3], 0, v[12:13]
	global_store_dwordx4 v[12:13], v[8:11], off
	s_nop 1
	v_ashrrev_i32_e32 v10, 3, v6
	v_lshl_add_u32 v6, v10, 1, v5
	ds_read_u16 v11, v6
	ds_read_u16 v12, v6 offset:516
	ds_read_u16 v7, v6 offset:1032
	ds_read_u16 v13, v6 offset:1548
	ds_read_u16 v8, v6 offset:2064
	ds_read_u16 v14, v6 offset:2580
	ds_read_u16 v9, v6 offset:3096
	ds_read_u16 v6, v6 offset:3612
	v_subrev_u32_e32 v10, s6, v10
	v_add_u32_e32 v10, s4, v10
	s_waitcnt lgkmcnt(2)
	v_perm_b32 v8, v14, v8, s34
	v_perm_b32 v7, v13, v7, s34
	s_waitcnt lgkmcnt(0)
	v_perm_b32 v9, v6, v9, s34
	v_perm_b32 v6, v12, v11, s34
	v_ashrrev_i32_e32 v11, 31, v10
	v_lshlrev_b64 v[10:11], 12, v[10:11]
	v_lshl_add_u64 v[10:11], v[2:3], 0, v[10:11]
	global_store_dwordx4 v[10:11], v[6:9], off
	s_nop 1
	v_ashrrev_i32_e32 v8, 3, v4
	v_lshl_add_u32 v4, v8, 1, v5
	ds_read_u16 v9, v4
	ds_read_u16 v10, v4 offset:516
	ds_read_u16 v5, v4 offset:1032
	ds_read_u16 v11, v4 offset:1548
	ds_read_u16 v6, v4 offset:2064
	ds_read_u16 v12, v4 offset:2580
	ds_read_u16 v7, v4 offset:3096
	ds_read_u16 v4, v4 offset:3612
	v_subrev_u32_e32 v8, s6, v8
	v_add_u32_e32 v8, s4, v8
	s_add_i32 s4, s4, s24
	s_waitcnt lgkmcnt(2)
	v_perm_b32 v6, v12, v6, s34
	s_waitcnt lgkmcnt(0)
	v_perm_b32 v7, v4, v7, s34
	v_perm_b32 v4, v10, v9, s34
	v_ashrrev_i32_e32 v9, 31, v8
	v_lshlrev_b64 v[8:9], 12, v[8:9]
	v_perm_b32 v5, v11, v5, s34
	v_lshl_add_u64 v[2:3], v[2:3], 0, v[8:9]
	s_cmpk_lt_i32 s5, 0x780
	global_store_dwordx4 v[2:3], v[4:7], off
	s_barrier
	s_cbranch_scc1 .LBB0_88

.LBB0_281:
	s_and_b32 s23, s34, 0xfffffe07
	s_and_b32 s27, s34, 0x38
	s_lshl_b32 s27, s27, 3
	s_or_b32 s23, s23, s27
	s_and_b32 s27, s34, 0x1c0
	s_lshr_b32 s27, s27, 3
	s_or_b32 s23, s23, s27
	s_lshr_b32 s0, s23, 1
	s_and_b32 s6, s0, 30
	s_ashr_i32 s4, s23, 9
	s_lshl_b32 s5, s4, 11
	s_lshl_b32 s1, s6, 6
	s_or_b32 s7, s1, s5
	s_lshl_b32 s1, s23, 4
	s_and_b32 s1, s1, 48
	s_or_b32 s7, s7, s1
	s_bfe_u32 s0, s23, 0x30006
	v_or_b32_e32 v184, s7, v192
	v_mov_b64_e32 v[30:31], s[50:51]
	v_mad_i64_i32 v[186:187], s[8:9], v184, s37, v[30:31]
	s_lshl_b32 s42, s0, 8
	v_or_b32_e32 v180, 64, v184
	v_mad_i64_i32 v[182:183], s[8:9], v180, s37, v[30:31]
	v_sub_u32_e64 v111, s6, 3 clamp
	v_sub_u32_e64 v112, s6, 4 clamp
	v_lshlrev_b32_e32 v194, 1, v170
	v_readfirstlane_b32 s6, v111
	v_readfirstlane_b32 s7, v112
	s_min_u32 s14, s6, 24
	s_min_u32 s15, s7, 24
	s_sub_i32 s59, s14, s15
	s_lshl_b32 s13, s0, 7
	s_add_i32 s2, s59, 8
	v_lshl_add_u64 v[2:3], v[186:187], 0, s[42:43]
	v_lshl_add_u64 v[4:5], v[182:183], 0, s[42:43]
	v_lshl_add_u64 v[2:3], v[2:3], 0, v[194:195]
	v_lshl_add_u64 v[4:5], v[4:5], 0, v[194:195]
	v_lshl_add_u64 v[2:3], v[2:3], 0, s[10:11]
	v_lshl_add_u64 v[4:5], v[4:5], 0, s[10:11]
	s_barrier
	s_bfe_u32 s27, s23, 0x30003
	s_lshl_b32 s27, s27, 2
	s_sub_i32 s42, s27, 4
	s_max_i32 s42, s42, 0
	s_min_i32 s32, s42, 24
	s_sub_i32 s42, s27, 1
	s_max_i32 s42, s42, 0
	s_min_i32 s42, s42, 24
	s_add_i32 s42, s42, 8
	s_sub_i32 s78, s42, s32
	s_mov_b32 s71, 0
	s_mov_b32 s98, 0x0
	s_mov_b32 s99, 0x0
	s_bfe_u32 s27, s12, 0x10001
	s_lshl_b32 s27, s27, 3
	v_lshrrev_b32_e32 v242, 1, v197
	v_sub_u32_e32 v243, v192, v242
	v_and_b32_e32 v243, 3, v243
	v_add_u32_e32 v244, v243, v242
	v_add_u32_e32 v244, s27, v244
	v_and_b32_e32 v244, 15, v244
	v_xor_b32_e32 v245, v192, v244
	v_and_b32_e32 v245, 12, v245
	v_or_b32_e32 v243, v243, v245
	v_lshlrev_b32_e32 v243, 4, v243
	v_lshrrev_b32_e32 v246, 2, v197
	s_lshl_b32 s27, s12, 2
	v_add_u32_e32 v246, s27, v246
	v_mul_u32_u24_e32 v246, 0x6800, v246
	v_add_u32_e32 v229, v246, v243
	v_or_b32_e32 v242, v172, v192
	v_lshrrev_b32_e32 v243, 3, v242
	v_and_b32_e32 v244, 6, v243
	v_and_b32_e32 v245, 7, v242
	v_sub_u32_e32 v245, v245, v244
	v_and_b32_e32 v245, 7, v245
	v_lshlrev_b32_e32 v245, 4, v245
	s_lshl_b32 s27, s12, 3
	v_add_u32_e32 v243, s27, v243
	v_mul_u32_u24_e32 v243, 0x9000, v243
	v_add_u32_e32 v254, v243, v245
	s_mov_b32 s9, 0
	s_sub_i32 s27, s9, s78
	s_lshr_b32 s42, s23, 9
	s_lshl_b32 s101, s42, 2
	s_add_i32 s27, s27, s101
	s_add_i32 s27, s27, 0x100
	s_lshl_b32 s42, s42, 5
	s_add_i32 s42, s42, s32
	s_add_i32 s42, s42, s9
	s_cmp_lt_u32 s9, s78
	s_cselect_b32 s27, s42, s27
	s_lshl_b32 s27, s27, 6
	s_mul_i32 s42, s27, s37
	s_add_u32 s10, s50, s42
	s_addc_u32 s11, s51, 0
	s_lshl_b32 s101, s13, 1
	s_add_i32 s101, s101, 0x2800
	s_add_u32 s10, s10, s101
	s_addc_u32 s11, s11, 0
	s_lshl_b32 s8, s12, 10
	s_add_i32 s8, s8, s98
	s_mov_b32 m0, s8
	s_add_i32 s8, s8, 0x2000
	global_load_lds_dwordx4 v229, s[10:11]
	s_mov_b32 m0, s8
	s_add_u32 s10, s10, 0xd0000
	s_addc_u32 s11, s11, 0
	global_load_lds_dwordx4 v229, s[10:11]
	v_readlane_b32 s10, v252, 55
	v_readlane_b32 s11, v252, 56
	s_mul_i32 s42, s13, 0x9000
	s_lshl_b32 s101, s27, 1
	s_add_i32 s42, s42, s101
	s_add_i32 s8, s8, 0x2000
	s_add_u32 s10, s10, s42
	s_addc_u32 s11, s11, 0
	s_mov_b32 m0, s8
	s_add_i32 s8, s8, 0x2000
	global_load_lds_dwordx4 v254, s[10:11]
	s_mov_b32 m0, s8
	s_add_u32 s10, s10, 0x240000
	s_addc_u32 s11, s11, 0
	global_load_lds_dwordx4 v254, s[10:11]
	s_add_i32 s98, s98, 0x8000
	s_cmp_eq_u32 s98, 0x18000
	s_cselect_b32 s98, 0x0, s98
	s_mov_b32 s9, 1
	s_sub_i32 s27, s9, s78
	s_lshr_b32 s42, s23, 9
	s_lshl_b32 s101, s42, 2
	s_add_i32 s27, s27, s101
	s_add_i32 s27, s27, 0x100
	s_lshl_b32 s42, s42, 5
	s_add_i32 s42, s42, s32
	s_add_i32 s42, s42, s9
	s_cmp_lt_u32 s9, s78
	s_cselect_b32 s27, s42, s27
	s_lshl_b32 s27, s27, 6
	s_mul_i32 s42, s27, s37
	s_add_u32 s10, s50, s42
	s_addc_u32 s11, s51, 0
	s_lshl_b32 s101, s13, 1
	s_add_i32 s101, s101, 0x2800
	s_add_u32 s10, s10, s101
	s_addc_u32 s11, s11, 0
	s_lshl_b32 s8, s12, 10
	s_add_i32 s8, s8, s98
	s_mov_b32 m0, s8
	s_add_i32 s8, s8, 0x2000
	global_load_lds_dwordx4 v229, s[10:11]
	s_mov_b32 m0, s8
	s_add_u32 s10, s10, 0xd0000
	s_addc_u32 s11, s11, 0
	global_load_lds_dwordx4 v229, s[10:11]
	v_readlane_b32 s10, v252, 55
	v_readlane_b32 s11, v252, 56
	s_mul_i32 s42, s13, 0x9000
	s_lshl_b32 s101, s27, 1
	s_add_i32 s42, s42, s101
	s_add_i32 s8, s8, 0x2000
	s_add_u32 s10, s10, s42
	s_addc_u32 s11, s11, 0
	s_mov_b32 m0, s8
	s_add_i32 s8, s8, 0x2000
	global_load_lds_dwordx4 v254, s[10:11]
	s_mov_b32 m0, s8
	s_add_u32 s10, s10, 0x240000
	s_addc_u32 s11, s11, 0
	global_load_lds_dwordx4 v254, s[10:11]
	s_add_i32 s98, s98, 0x8000
	s_cmp_eq_u32 s98, 0x18000
	s_cselect_b32 s98, 0x0, s98
	s_and_b32 s27, s23, 3
	s_lshl_b32 s27, s27, 4
	s_sub_i32 s27, s27, 8
	s_max_i32 s27, s27, 0
	s_min_i32 s42, s27, 32
	s_lshr_b32 s101, s42, 3
	v_lshrrev_b32_e32 v242, 2, v192
	v_and_b32_e32 v243, 3, v192
	v_lshl_add_u32 v244, v242, 3, v243
	v_add_u32_e32 v245, s42, v244
	v_add_u32_e32 v246, s101, v242
	v_and_b32_e32 v246, 1, v246
	v_lshl_or_b32 v246, v246, 2, v243
	v_lshrrev_b32_e32 v247, 2, v197
	v_lshl_add_u32 v246, v246, 1, v247
	v_and_b32_e32 v246, 15, v246
	v_lshlrev_b32_e32 v246, 4, v246
	v_lshl_add_u32 v255, v245, 8, v246
	v_and_b32_e32 v246, 1, v242
	v_lshl_or_b32 v246, v246, 2, v243
	v_lshl_add_u32 v246, v246, 1, v247
	v_and_b32_e32 v246, 15, v246
	v_lshlrev_b32_e32 v246, 4, v246
	v_lshl_add_u32 v190, v244, 8, v246
	v_and_b32_e32 v242, 14, v192
	v_add_u32_e32 v242, v242, v247
	v_lshlrev_b32_e32 v243, 7, v192
	v_add_u32_e32 v243, 0x4000, v243
	v_add_u32_e32 v244, s101, v242
	v_and_b32_e32 v244, 7, v244
	v_lshl_add_u32 v191, v244, 4, v243
	v_and_b32_e32 v244, 7, v242
	v_lshl_add_u32 v181, v244, 4, v243
	v_add_u32_e32 v244, 4, v242
	v_and_b32_e32 v244, 7, v244
	v_lshl_add_u32 v249, v244, 4, v243
	global_load_dwordx4 v[146:149], v[2:3], off
	global_load_dwordx4 v[150:153], v[2:3], off offset:64
	global_load_dwordx4 v[154:157], v[2:3], off offset:128
	global_load_dwordx4 v[158:161], v[2:3], off offset:192
	global_load_dwordx4 v[98:101], v[4:5], off
	global_load_dwordx4 v[102:105], v[4:5], off offset:64
	global_load_dwordx4 v[106:109], v[4:5], off offset:128
	global_load_dwordx4 v[110:113], v[4:5], off offset:192
	global_load_dwordx4 v[114:117], v[176:177], off
	global_load_dwordx4 v[118:121], v[176:177], off offset:16
	global_load_dwordx4 v[122:125], v[176:177], off offset:128
	global_load_dwordx4 v[126:129], v[176:177], off offset:144
	global_load_dwordx4 v[130:133], v[176:177], off offset:256
	global_load_dwordx4 v[134:137], v[176:177], off offset:272
	global_load_dwordx4 v[138:141], v[176:177], off offset:384
	global_load_dwordx4 v[142:145], v[176:177], off offset:400
	s_waitcnt vmcnt(8)
	v_lshlrev_b32_e32 v8, 16, v146
	v_lshlrev_b32_e32 v9, 16, v98
	v_and_b32_e32 v10, 0xffff0000, v146
	v_and_b32_e32 v11, 0xffff0000, v98
	v_mul_f32_e32 v6, v8, v8
	v_mul_f32_e32 v7, v9, v9
	v_fmac_f32_e32 v6, v10, v10
	v_fmac_f32_e32 v7, v11, v11
	v_lshlrev_b32_e32 v8, 16, v147
	v_lshlrev_b32_e32 v9, 16, v99
	v_and_b32_e32 v10, 0xffff0000, v147
	v_and_b32_e32 v11, 0xffff0000, v99
	v_fmac_f32_e32 v6, v8, v8
	v_fmac_f32_e32 v7, v9, v9
	v_fmac_f32_e32 v6, v10, v10
	v_fmac_f32_e32 v7, v11, v11
	v_lshlrev_b32_e32 v8, 16, v148
	v_lshlrev_b32_e32 v9, 16, v100
	v_and_b32_e32 v10, 0xffff0000, v148
	v_and_b32_e32 v11, 0xffff0000, v100
	v_fmac_f32_e32 v6, v8, v8
	v_fmac_f32_e32 v7, v9, v9
	v_fmac_f32_e32 v6, v10, v10
	v_fmac_f32_e32 v7, v11, v11
	v_lshlrev_b32_e32 v8, 16, v149
	v_lshlrev_b32_e32 v9, 16, v101
	v_and_b32_e32 v10, 0xffff0000, v149
	v_and_b32_e32 v11, 0xffff0000, v101
	v_fmac_f32_e32 v6, v8, v8
	v_fmac_f32_e32 v7, v9, v9
	v_fmac_f32_e32 v6, v10, v10
	v_fmac_f32_e32 v7, v11, v11
	v_lshlrev_b32_e32 v8, 16, v150
	v_lshlrev_b32_e32 v9, 16, v102
	v_and_b32_e32 v10, 0xffff0000, v150
	v_and_b32_e32 v11, 0xffff0000, v102
	v_fmac_f32_e32 v6, v8, v8
	v_fmac_f32_e32 v7, v9, v9
	v_fmac_f32_e32 v6, v10, v10
	v_fmac_f32_e32 v7, v11, v11
	v_lshlrev_b32_e32 v8, 16, v151
	v_lshlrev_b32_e32 v9, 16, v103
	v_and_b32_e32 v10, 0xffff0000, v151
	v_and_b32_e32 v11, 0xffff0000, v103
	v_fmac_f32_e32 v6, v8, v8
	v_fmac_f32_e32 v7, v9, v9
	v_fmac_f32_e32 v6, v10, v10
	v_fmac_f32_e32 v7, v11, v11
	v_lshlrev_b32_e32 v8, 16, v152
	v_lshlrev_b32_e32 v9, 16, v104
	v_and_b32_e32 v10, 0xffff0000, v152
	v_and_b32_e32 v11, 0xffff0000, v104
	v_fmac_f32_e32 v6, v8, v8
	v_fmac_f32_e32 v7, v9, v9
	v_fmac_f32_e32 v6, v10, v10
	v_fmac_f32_e32 v7, v11, v11
	v_lshlrev_b32_e32 v8, 16, v153
	v_lshlrev_b32_e32 v9, 16, v105
	v_and_b32_e32 v10, 0xffff0000, v153
	v_and_b32_e32 v11, 0xffff0000, v105
	v_fmac_f32_e32 v6, v8, v8
	v_fmac_f32_e32 v7, v9, v9
	v_fmac_f32_e32 v6, v10, v10
	v_fmac_f32_e32 v7, v11, v11
	v_lshlrev_b32_e32 v8, 16, v154
	v_lshlrev_b32_e32 v9, 16, v106
	v_and_b32_e32 v10, 0xffff0000, v154
	v_and_b32_e32 v11, 0xffff0000, v106
	v_fmac_f32_e32 v6, v8, v8
	v_fmac_f32_e32 v7, v9, v9
	v_fmac_f32_e32 v6, v10, v10
	v_fmac_f32_e32 v7, v11, v11
	v_lshlrev_b32_e32 v8, 16, v155
	v_lshlrev_b32_e32 v9, 16, v107
	v_and_b32_e32 v10, 0xffff0000, v155
	v_and_b32_e32 v11, 0xffff0000, v107
	v_fmac_f32_e32 v6, v8, v8
	v_fmac_f32_e32 v7, v9, v9
	v_fmac_f32_e32 v6, v10, v10
	v_fmac_f32_e32 v7, v11, v11
	v_lshlrev_b32_e32 v8, 16, v156
	v_lshlrev_b32_e32 v9, 16, v108
	v_and_b32_e32 v10, 0xffff0000, v156
	v_and_b32_e32 v11, 0xffff0000, v108
	v_fmac_f32_e32 v6, v8, v8
	v_fmac_f32_e32 v7, v9, v9
	v_fmac_f32_e32 v6, v10, v10
	v_fmac_f32_e32 v7, v11, v11
	v_lshlrev_b32_e32 v8, 16, v157
	v_lshlrev_b32_e32 v9, 16, v109
	v_and_b32_e32 v10, 0xffff0000, v157
	v_and_b32_e32 v11, 0xffff0000, v109
	v_fmac_f32_e32 v6, v8, v8
	v_fmac_f32_e32 v7, v9, v9
	v_fmac_f32_e32 v6, v10, v10
	v_fmac_f32_e32 v7, v11, v11
	v_lshlrev_b32_e32 v8, 16, v158
	v_lshlrev_b32_e32 v9, 16, v110
	v_and_b32_e32 v10, 0xffff0000, v158
	v_and_b32_e32 v11, 0xffff0000, v110
	v_fmac_f32_e32 v6, v8, v8
	v_fmac_f32_e32 v7, v9, v9
	v_fmac_f32_e32 v6, v10, v10
	v_fmac_f32_e32 v7, v11, v11
	v_lshlrev_b32_e32 v8, 16, v159
	v_lshlrev_b32_e32 v9, 16, v111
	v_and_b32_e32 v10, 0xffff0000, v159
	v_and_b32_e32 v11, 0xffff0000, v111
	v_fmac_f32_e32 v6, v8, v8
	v_fmac_f32_e32 v7, v9, v9
	v_fmac_f32_e32 v6, v10, v10
	v_fmac_f32_e32 v7, v11, v11
	v_lshlrev_b32_e32 v8, 16, v160
	v_lshlrev_b32_e32 v9, 16, v112
	v_and_b32_e32 v10, 0xffff0000, v160
	v_and_b32_e32 v11, 0xffff0000, v112
	v_fmac_f32_e32 v6, v8, v8
	v_fmac_f32_e32 v7, v9, v9
	v_fmac_f32_e32 v6, v10, v10
	v_fmac_f32_e32 v7, v11, v11
	v_lshlrev_b32_e32 v8, 16, v161
	v_lshlrev_b32_e32 v9, 16, v113
	v_and_b32_e32 v10, 0xffff0000, v161
	v_and_b32_e32 v11, 0xffff0000, v113
	v_fmac_f32_e32 v6, v8, v8
	v_fmac_f32_e32 v7, v9, v9
	v_fmac_f32_e32 v6, v10, v10
	v_fmac_f32_e32 v7, v11, v11
	ds_bpermute_b32 v8, v171, v6
	ds_bpermute_b32 v9, v171, v7
	s_waitcnt lgkmcnt(0)
	v_add_f32_e32 v6, v6, v8
	v_add_f32_e32 v7, v7, v9
	ds_bpermute_b32 v8, v199, v6
	ds_bpermute_b32 v9, v199, v7
	s_waitcnt lgkmcnt(0)
	v_add_f32_e32 v6, v6, v8
	v_add_f32_e32 v7, v7, v9
	v_fmamk_f32 v6, v6, 0x3c000000, v230
	v_mul_f32_e32 v8, 0x4b800000, v6
	v_cmp_gt_f32_e32 vcc, s70, v6
	s_nop 1
	v_cndmask_b32_e32 v6, v6, v8, vcc
	v_rsq_f32_e32 v14, v6
	s_nop 0
	v_mul_f32_e32 v8, 0x45800000, v14
	v_cndmask_b32_e32 v14, v14, v8, vcc
	v_mul_f32_e32 v14, 0x3db504f3, v14
	v_fmamk_f32 v7, v7, 0x3c000000, v230
	v_mul_f32_e32 v9, 0x4b800000, v7
	v_cmp_gt_f32_e32 vcc, s70, v7
	s_nop 1
	v_cndmask_b32_e32 v7, v7, v9, vcc
	v_rsq_f32_e32 v15, v7
	s_nop 0
	v_mul_f32_e32 v9, 0x45800000, v15
	v_cndmask_b32_e32 v15, v15, v9, vcc
	v_mul_f32_e32 v15, 0x3db504f3, v15
	s_waitcnt vmcnt(0)
	v_lshlrev_b32_e32 v16, 16, v146
	v_and_b32_e32 v17, 0xffff0000, v146
	v_mul_f32_e32 v16, v14, v16
	v_mul_f32_e32 v17, v14, v17
	v_mul_f32_e32 v16, v114, v16
	v_mul_f32_e32 v17, v115, v17
	v_cvt_pk_bf16_f32 v50, v16, v17
	v_lshlrev_b32_e32 v16, 16, v147
	v_and_b32_e32 v17, 0xffff0000, v147
	v_mul_f32_e32 v16, v14, v16
	v_mul_f32_e32 v17, v14, v17
	v_mul_f32_e32 v16, v116, v16
	v_mul_f32_e32 v17, v117, v17
	v_cvt_pk_bf16_f32 v51, v16, v17
	v_lshlrev_b32_e32 v16, 16, v148
	v_and_b32_e32 v17, 0xffff0000, v148
	v_mul_f32_e32 v16, v14, v16
	v_mul_f32_e32 v17, v14, v17
	v_mul_f32_e32 v16, v118, v16
	v_mul_f32_e32 v17, v119, v17
	v_cvt_pk_bf16_f32 v52, v16, v17
	v_lshlrev_b32_e32 v16, 16, v149
	v_and_b32_e32 v17, 0xffff0000, v149
	v_mul_f32_e32 v16, v14, v16
	v_mul_f32_e32 v17, v14, v17
	v_mul_f32_e32 v16, v120, v16
	v_mul_f32_e32 v17, v121, v17
	v_cvt_pk_bf16_f32 v53, v16, v17
	v_lshlrev_b32_e32 v16, 16, v98
	v_and_b32_e32 v17, 0xffff0000, v98
	v_mul_f32_e32 v16, v15, v16
	v_mul_f32_e32 v17, v15, v17
	v_mul_f32_e32 v16, v114, v16
	v_mul_f32_e32 v17, v115, v17
	v_cvt_pk_bf16_f32 v78, v16, v17
	v_lshlrev_b32_e32 v16, 16, v99
	v_and_b32_e32 v17, 0xffff0000, v99
	v_mul_f32_e32 v16, v15, v16
	v_mul_f32_e32 v17, v15, v17
	v_mul_f32_e32 v16, v116, v16
	v_mul_f32_e32 v17, v117, v17
	v_cvt_pk_bf16_f32 v79, v16, v17
	v_lshlrev_b32_e32 v16, 16, v100
	v_and_b32_e32 v17, 0xffff0000, v100
	v_mul_f32_e32 v16, v15, v16
	v_mul_f32_e32 v17, v15, v17
	v_mul_f32_e32 v16, v118, v16
	v_mul_f32_e32 v17, v119, v17
	v_cvt_pk_bf16_f32 v80, v16, v17
	v_lshlrev_b32_e32 v16, 16, v101
	v_and_b32_e32 v17, 0xffff0000, v101
	v_mul_f32_e32 v16, v15, v16
	v_mul_f32_e32 v17, v15, v17
	v_mul_f32_e32 v16, v120, v16
	v_mul_f32_e32 v17, v121, v17
	v_cvt_pk_bf16_f32 v81, v16, v17
	v_lshlrev_b32_e32 v16, 16, v150
	v_and_b32_e32 v17, 0xffff0000, v150
	v_mul_f32_e32 v16, v14, v16
	v_mul_f32_e32 v17, v14, v17
	v_mul_f32_e32 v16, v122, v16
	v_mul_f32_e32 v17, v123, v17
	v_cvt_pk_bf16_f32 v54, v16, v17
	v_lshlrev_b32_e32 v16, 16, v151
	v_and_b32_e32 v17, 0xffff0000, v151
	v_mul_f32_e32 v16, v14, v16
	v_mul_f32_e32 v17, v14, v17
	v_mul_f32_e32 v16, v124, v16
	v_mul_f32_e32 v17, v125, v17
	v_cvt_pk_bf16_f32 v55, v16, v17
	v_lshlrev_b32_e32 v16, 16, v152
	v_and_b32_e32 v17, 0xffff0000, v152
	v_mul_f32_e32 v16, v14, v16
	v_mul_f32_e32 v17, v14, v17
	v_mul_f32_e32 v16, v126, v16
	v_mul_f32_e32 v17, v127, v17
	v_cvt_pk_bf16_f32 v56, v16, v17
	v_lshlrev_b32_e32 v16, 16, v153
	v_and_b32_e32 v17, 0xffff0000, v153
	v_mul_f32_e32 v16, v14, v16
	v_mul_f32_e32 v17, v14, v17
	v_mul_f32_e32 v16, v128, v16
	v_mul_f32_e32 v17, v129, v17
	v_cvt_pk_bf16_f32 v57, v16, v17
	v_lshlrev_b32_e32 v16, 16, v102
	v_and_b32_e32 v17, 0xffff0000, v102
	v_mul_f32_e32 v16, v15, v16
	v_mul_f32_e32 v17, v15, v17
	v_mul_f32_e32 v16, v122, v16
	v_mul_f32_e32 v17, v123, v17
	v_cvt_pk_bf16_f32 v82, v16, v17
	v_lshlrev_b32_e32 v16, 16, v103
	v_and_b32_e32 v17, 0xffff0000, v103
	v_mul_f32_e32 v16, v15, v16
	v_mul_f32_e32 v17, v15, v17
	v_mul_f32_e32 v16, v124, v16
	v_mul_f32_e32 v17, v125, v17
	v_cvt_pk_bf16_f32 v83, v16, v17
	v_lshlrev_b32_e32 v16, 16, v104
	v_and_b32_e32 v17, 0xffff0000, v104
	v_mul_f32_e32 v16, v15, v16
	v_mul_f32_e32 v17, v15, v17
	v_mul_f32_e32 v16, v126, v16
	v_mul_f32_e32 v17, v127, v17
	v_cvt_pk_bf16_f32 v84, v16, v17
	v_lshlrev_b32_e32 v16, 16, v105
	v_and_b32_e32 v17, 0xffff0000, v105
	v_mul_f32_e32 v16, v15, v16
	v_mul_f32_e32 v17, v15, v17
	v_mul_f32_e32 v16, v128, v16
	v_mul_f32_e32 v17, v129, v17
	v_cvt_pk_bf16_f32 v85, v16, v17
	v_lshlrev_b32_e32 v16, 16, v154
	v_and_b32_e32 v17, 0xffff0000, v154
	v_mul_f32_e32 v16, v14, v16
	v_mul_f32_e32 v17, v14, v17
	v_mul_f32_e32 v16, v130, v16
	v_mul_f32_e32 v17, v131, v17
	v_cvt_pk_bf16_f32 v58, v16, v17
	v_lshlrev_b32_e32 v16, 16, v155
	v_and_b32_e32 v17, 0xffff0000, v155
	v_mul_f32_e32 v16, v14, v16
	v_mul_f32_e32 v17, v14, v17
	v_mul_f32_e32 v16, v132, v16
	v_mul_f32_e32 v17, v133, v17
	v_cvt_pk_bf16_f32 v59, v16, v17
	v_lshlrev_b32_e32 v16, 16, v156
	v_and_b32_e32 v17, 0xffff0000, v156
	v_mul_f32_e32 v16, v14, v16
	v_mul_f32_e32 v17, v14, v17
	v_mul_f32_e32 v16, v134, v16
	v_mul_f32_e32 v17, v135, v17
	v_cvt_pk_bf16_f32 v60, v16, v17
	v_lshlrev_b32_e32 v16, 16, v157
	v_and_b32_e32 v17, 0xffff0000, v157
	v_mul_f32_e32 v16, v14, v16
	v_mul_f32_e32 v17, v14, v17
	v_mul_f32_e32 v16, v136, v16
	v_mul_f32_e32 v17, v137, v17
	v_cvt_pk_bf16_f32 v61, v16, v17
	v_lshlrev_b32_e32 v16, 16, v106
	v_and_b32_e32 v17, 0xffff0000, v106
	v_mul_f32_e32 v16, v15, v16
	v_mul_f32_e32 v17, v15, v17
	v_mul_f32_e32 v16, v130, v16
	v_mul_f32_e32 v17, v131, v17
	v_cvt_pk_bf16_f32 v86, v16, v17
	v_lshlrev_b32_e32 v16, 16, v107
	v_and_b32_e32 v17, 0xffff0000, v107
	v_mul_f32_e32 v16, v15, v16
	v_mul_f32_e32 v17, v15, v17
	v_mul_f32_e32 v16, v132, v16
	v_mul_f32_e32 v17, v133, v17
	v_cvt_pk_bf16_f32 v87, v16, v17
	v_lshlrev_b32_e32 v16, 16, v108
	v_and_b32_e32 v17, 0xffff0000, v108
	v_mul_f32_e32 v16, v15, v16
	v_mul_f32_e32 v17, v15, v17
	v_mul_f32_e32 v16, v134, v16
	v_mul_f32_e32 v17, v135, v17
	v_cvt_pk_bf16_f32 v88, v16, v17
	v_lshlrev_b32_e32 v16, 16, v109
	v_and_b32_e32 v17, 0xffff0000, v109
	v_mul_f32_e32 v16, v15, v16
	v_mul_f32_e32 v17, v15, v17
	v_mul_f32_e32 v16, v136, v16
	v_mul_f32_e32 v17, v137, v17
	v_cvt_pk_bf16_f32 v89, v16, v17
	v_lshlrev_b32_e32 v16, 16, v158
	v_and_b32_e32 v17, 0xffff0000, v158
	v_mul_f32_e32 v16, v14, v16
	v_mul_f32_e32 v17, v14, v17
	v_mul_f32_e32 v16, v138, v16
	v_mul_f32_e32 v17, v139, v17
	v_cvt_pk_bf16_f32 v66, v16, v17
	v_lshlrev_b32_e32 v16, 16, v159
	v_and_b32_e32 v17, 0xffff0000, v159
	v_mul_f32_e32 v16, v14, v16
	v_mul_f32_e32 v17, v14, v17
	v_mul_f32_e32 v16, v140, v16
	v_mul_f32_e32 v17, v141, v17
	v_cvt_pk_bf16_f32 v67, v16, v17
	v_lshlrev_b32_e32 v16, 16, v160
	v_and_b32_e32 v17, 0xffff0000, v160
	v_mul_f32_e32 v16, v14, v16
	v_mul_f32_e32 v17, v14, v17
	v_mul_f32_e32 v16, v142, v16
	v_mul_f32_e32 v17, v143, v17
	v_cvt_pk_bf16_f32 v68, v16, v17
	v_lshlrev_b32_e32 v16, 16, v161
	v_and_b32_e32 v17, 0xffff0000, v161
	v_mul_f32_e32 v16, v14, v16
	v_mul_f32_e32 v17, v14, v17
	v_mul_f32_e32 v16, v144, v16
	v_mul_f32_e32 v17, v145, v17
	v_cvt_pk_bf16_f32 v69, v16, v17
	v_lshlrev_b32_e32 v16, 16, v110
	v_and_b32_e32 v17, 0xffff0000, v110
	v_mul_f32_e32 v16, v15, v16
	v_mul_f32_e32 v17, v15, v17
	v_mul_f32_e32 v16, v138, v16
	v_mul_f32_e32 v17, v139, v17
	v_cvt_pk_bf16_f32 v94, v16, v17
	v_lshlrev_b32_e32 v16, 16, v111
	v_and_b32_e32 v17, 0xffff0000, v111
	v_mul_f32_e32 v16, v15, v16
	v_mul_f32_e32 v17, v15, v17
	v_mul_f32_e32 v16, v140, v16
	v_mul_f32_e32 v17, v141, v17
	v_cvt_pk_bf16_f32 v95, v16, v17
	v_lshlrev_b32_e32 v16, 16, v112
	v_and_b32_e32 v17, 0xffff0000, v112
	v_mul_f32_e32 v16, v15, v16
	v_mul_f32_e32 v17, v15, v17
	v_mul_f32_e32 v16, v142, v16
	v_mul_f32_e32 v17, v143, v17
	v_cvt_pk_bf16_f32 v96, v16, v17
	v_lshlrev_b32_e32 v16, 16, v113
	v_and_b32_e32 v17, 0xffff0000, v113
	v_mul_f32_e32 v16, v15, v16
	v_mul_f32_e32 v17, v15, v17
	v_mul_f32_e32 v16, v144, v16
	v_mul_f32_e32 v17, v145, v17
	v_cvt_pk_bf16_f32 v97, v16, v17
	s_bfe_u32 s6, s23, 0x40002
	s_lshl_b32 s7, s6, 1
	v_sub_u32_e64 v2, s7, 4 clamp
	s_and_b32 s10, s26, 48
	v_readfirstlane_b32 s8, v2
	v_sub_u32_e64 v2, s7, 3 clamp
	s_min_u32 s3, s8, 24
	v_readfirstlane_b32 s7, v2
	v_sub_u32_e64 v2, s10, 8 clamp
	v_min_u32_e32 v2, 32, v2
	s_mul_i32 s11, s3, 31
	v_add_u32_e32 v2, s11, v2
	v_add_u32_e32 v2, v2, v173
	v_subrev_u32_e32 v2, s10, v2
	s_mul_i32 s6, s6, 62
	v_subrev_u32_e32 v188, s6, v2
	v_sub_u32_e64 v2, s1, 8 clamp
	s_min_u32 s7, s7, 24
	v_min_u32_e32 v4, 32, v2
	v_or_b32_e32 v2, s1, v192
	s_sub_i32 s6, s7, s3
	v_sub_u32_e64 v2, v2, 8 clamp
	s_add_i32 s6, s6, 15
	s_or_b32 s0, s0, s17
	v_min_u32_e32 v5, 48, v2
	v_or_b32_e32 v2, s13, v192
	s_mul_i32 s42, s0, 0x1d1
	v_readlane_b32 s52, v252, 12
	v_mul_u32_u24_e32 v2, 0x4800, v2
	s_lshl_b32 s8, s3, 5
	s_lshl_b32 s9, s7, 5
	s_lshl_b64 s[0:1], s[42:43], 2
	v_readlane_b32 s64, v252, 24
	v_lshlrev_b32_e32 v2, 1, v2
	v_mov_b32_e32 v3, v195
	v_readlane_b32 s65, v252, 25
	s_add_u32 s0, s64, s0
	v_add_u32_e32 v2, v4, v170
	v_add_u32_e32 v3, 16, v5
	s_addc_u32 s1, s65, s1
	s_lshl_b32 s10, s4, 8
	v_cmp_ge_u32_e32 vcc, v2, v5
	v_cmp_lt_u32_e64 s[4:5], v2, v3
	v_or_b32_e32 v4, 1, v2
	v_readlane_b32 s53, v252, 13
	s_and_b64 s[40:41], vcc, s[4:5]
	v_cmp_ge_u32_e32 vcc, v4, v5
	v_cmp_lt_u32_e64 s[4:5], v4, v3
	v_or_b32_e32 v4, 2, v2
	v_readlane_b32 s54, v252, 14
	v_readlane_b32 s55, v252, 15
	s_and_b64 s[52:53], vcc, s[4:5]
	v_cmp_ge_u32_e32 vcc, v4, v5
	v_cmp_lt_u32_e64 s[4:5], v4, v3
	v_or_b32_e32 v4, 3, v2
	v_readlane_b32 s60, v252, 20
	v_readlane_b32 s61, v252, 21
	s_and_b64 s[54:55], vcc, s[4:5]
	v_cmp_ge_u32_e32 vcc, v4, v5
	v_cmp_lt_u32_e64 s[4:5], v4, v3
	v_or_b32_e32 v4, 4, v2
	v_readlane_b32 s62, v252, 22
	v_readlane_b32 s63, v252, 23
	s_and_b64 s[60:61], vcc, s[4:5]
	v_cmp_ge_u32_e32 vcc, v4, v5
	v_cmp_lt_u32_e64 s[4:5], v4, v3
	v_or_b32_e32 v4, 5, v2
	s_and_b64 s[62:63], vcc, s[4:5]
	v_cmp_ge_u32_e32 vcc, v4, v5
	v_cmp_lt_u32_e64 s[4:5], v4, v3
	v_or_b32_e32 v4, 6, v2
	s_and_b64 s[80:81], vcc, s[4:5]
	v_cmp_ge_u32_e32 vcc, v4, v5
	v_cmp_lt_u32_e64 s[4:5], v4, v3
	v_or_b32_e32 v2, 7, v2
	s_and_b64 s[82:83], vcc, s[4:5]
	v_cmp_ge_u32_e32 vcc, v2, v5
	v_cmp_lt_u32_e64 s[4:5], v2, v3
	s_add_i32 s10, s10, s8
	s_and_b64 s[6:7], vcc, s[4:5]
	s_sub_i32 s4, s10, s9
	v_mov_b32_e32 v175, 0
	s_mov_b32 s70, 0
	v_mov_b32_e32 v253, 0xff800000
	s_movk_i32 s22, 0x1d0
	v_mov_b32_e32 v185, 0xff800000
	v_mov_b32_e32 v203, 0xff800000
	v_mov_b32_e32 v201, 0
	v_mov_b32_e32 v34, 0
	v_mov_b32_e32 v35, v175
	v_mov_b32_e32 v36, v175
	v_mov_b32_e32 v37, v175
	v_mov_b32_e32 v38, 0
	v_mov_b32_e32 v39, v175
	v_mov_b32_e32 v40, v175
	v_mov_b32_e32 v41, v175
	v_mov_b32_e32 v42, 0
	v_mov_b32_e32 v43, v175
	v_mov_b32_e32 v44, v175
	v_mov_b32_e32 v45, v175
	v_mov_b32_e32 v46, 0
	v_mov_b32_e32 v47, v175
	v_mov_b32_e32 v48, v175
	v_mov_b32_e32 v49, v175
	v_mov_b32_e32 v62, 0
	v_mov_b32_e32 v63, v175
	v_mov_b32_e32 v64, v175
	v_mov_b32_e32 v65, v175
	v_mov_b32_e32 v70, 0
	v_mov_b32_e32 v71, v175
	v_mov_b32_e32 v72, v175
	v_mov_b32_e32 v73, v175
	v_mov_b32_e32 v74, 0
	v_mov_b32_e32 v75, v175
	v_mov_b32_e32 v76, v175
	v_mov_b32_e32 v77, v175
	v_mov_b32_e32 v90, 0
	v_mov_b32_e32 v91, v175
	v_mov_b32_e32 v92, v175
	v_mov_b32_e32 v93, v175
	v_mov_b32_e32 v30, 0
	v_mov_b32_e32 v31, v175
	v_mov_b32_e32 v32, v175
	v_mov_b32_e32 v33, v175
	v_mov_b32_e32 v26, 0
	v_mov_b32_e32 v27, v175
	v_mov_b32_e32 v28, v175
	v_mov_b32_e32 v29, v175
	v_mov_b32_e32 v22, 0
	v_mov_b32_e32 v23, v175
	v_mov_b32_e32 v24, v175
	v_mov_b32_e32 v25, v175
	v_mov_b32_e32 v18, 0
	v_mov_b32_e32 v19, v175
	v_mov_b32_e32 v20, v175
	v_mov_b32_e32 v21, v175
	v_mov_b32_e32 v14, 0
	v_mov_b32_e32 v15, v175
	v_mov_b32_e32 v16, v175
	v_mov_b32_e32 v17, v175
	v_mov_b32_e32 v10, 0
	v_mov_b32_e32 v11, v175
	v_mov_b32_e32 v12, v175
	v_mov_b32_e32 v13, v175
	v_mov_b32_e32 v6, 0
	v_mov_b32_e32 v7, v175
	v_mov_b32_e32 v8, v175
	v_mov_b32_e32 v9, v175
	v_mov_b32_e32 v2, 0
	v_mov_b32_e32 v3, v175
	v_mov_b32_e32 v4, v175
	v_mov_b32_e32 v5, v175
	v_readlane_b32 s56, v252, 16
	v_readlane_b32 s57, v252, 17
	v_readlane_b32 s58, v252, 18
	v_readlane_b32 s59, v252, 19
	v_readlane_b32 s66, v252, 26
	v_readlane_b32 s67, v252, 27

.Lat_loc_dma:
	s_add_i32 s9, s71, 2
	s_sub_i32 s27, s9, s78
	s_lshr_b32 s42, s23, 9
	s_lshl_b32 s101, s42, 2
	s_add_i32 s27, s27, s101
	s_add_i32 s27, s27, 0x100
	s_lshl_b32 s42, s42, 5
	s_add_i32 s42, s42, s32
	s_add_i32 s42, s42, s9
	s_cmp_lt_u32 s9, s78
	s_cselect_b32 s27, s42, s27
	s_lshl_b32 s27, s27, 6
	s_mul_i32 s42, s27, s37
	s_add_u32 s10, s50, s42
	s_addc_u32 s11, s51, 0
	s_lshl_b32 s101, s13, 1
	s_add_i32 s101, s101, 0x2800
	s_add_u32 s10, s10, s101
	s_addc_u32 s11, s11, 0
	s_lshl_b32 s8, s12, 10
	s_add_i32 s8, s8, s98
	s_mov_b32 m0, s8
	s_add_i32 s8, s8, 0x2000
	global_load_lds_dwordx4 v229, s[10:11]
	s_mov_b32 m0, s8
	s_add_u32 s10, s10, 0xd0000
	s_addc_u32 s11, s11, 0
	global_load_lds_dwordx4 v229, s[10:11]
	v_readlane_b32 s10, v252, 55
	v_readlane_b32 s11, v252, 56
	s_mul_i32 s42, s13, 0x9000
	s_lshl_b32 s101, s27, 1
	s_add_i32 s42, s42, s101
	s_add_i32 s8, s8, 0x2000
	s_add_u32 s10, s10, s42
	s_addc_u32 s11, s11, 0
	s_mov_b32 m0, s8
	s_add_i32 s8, s8, 0x2000
	global_load_lds_dwordx4 v254, s[10:11]
	s_mov_b32 m0, s8
	s_add_u32 s10, s10, 0x240000
	s_addc_u32 s11, s11, 0
	global_load_lds_dwordx4 v254, s[10:11]
	s_add_i32 s98, s98, 0x8000
	s_cmp_eq_u32 s98, 0x18000
	s_cselect_b32 s98, 0x0, s98
	s_cmp_eq_u32 s100, 0
	s_cbranch_scc1 .Lat_tile_next
	v_add_u32_e32 v242, s99, v255
	v_xor_b32_e32 v243, 64, v255
	v_xor_b32_e32 v244, 0x80, v255
	v_xor_b32_e32 v245, 0xc0, v255
	v_add_u32_e32 v243, s99, v243
	v_add_u32_e32 v244, s99, v244
	v_add_u32_e32 v245, s99, v245
	v_add_u32_e32 v246, s99, v191
	ds_read_b128 v[142:145], v242
	ds_read_b128 v[130:133], v243
	ds_read_b128 v[134:137], v244
	ds_read_b128 v[138:141], v245
	ds_read_b128 v[158:161], v242 offset:1024
	ds_read_b128 v[150:153], v243 offset:1024
	ds_read_b128 v[154:157], v244 offset:1024
	ds_read_b128 v[146:149], v245 offset:1024
	ds_read_b128 v[126:129], v246
	ds_read_b128 v[122:125], v246 offset:2048
	ds_read_b128 v[118:121], v246 offset:4096
	ds_read_b128 v[114:117], v246 offset:6144
	ds_read_b128 v[110:113], v246 offset:8192
	ds_read_b128 v[106:109], v246 offset:10240
	ds_read_b128 v[102:105], v246 offset:12288
	ds_read_b128 v[98:101], v246 offset:14336
	s_mov_b32 s100, 2
	s_branch .Lat_body
.Lat_ctx_tile:
	s_add_i32 s9, s71, 2
	s_add_i32 s42, s78, 4
	s_cmp_lt_u32 s9, s42
	s_cbranch_scc0 .Lat_ctx_nodma
	s_sub_i32 s27, s9, s78
	s_lshr_b32 s42, s23, 9
	s_lshl_b32 s101, s42, 2
	s_add_i32 s27, s27, s101
	s_add_i32 s27, s27, 0x100
	s_lshl_b32 s42, s42, 5
	s_add_i32 s42, s42, s32
	s_add_i32 s42, s42, s9
	s_cmp_lt_u32 s9, s78
	s_cselect_b32 s27, s42, s27
	s_lshl_b32 s27, s27, 6
	s_mul_i32 s42, s27, s37
	s_add_u32 s10, s50, s42
	s_addc_u32 s11, s51, 0
	s_lshl_b32 s101, s13, 1
	s_add_i32 s101, s101, 0x2800
	s_add_u32 s10, s10, s101
	s_addc_u32 s11, s11, 0
	s_lshl_b32 s8, s12, 10
	s_add_i32 s8, s8, s98
	s_mov_b32 m0, s8
	s_add_i32 s8, s8, 0x2000
	global_load_lds_dwordx4 v229, s[10:11]
	s_mov_b32 m0, s8
	s_add_u32 s10, s10, 0xd0000
	s_addc_u32 s11, s11, 0
	global_load_lds_dwordx4 v229, s[10:11]
	v_readlane_b32 s10, v252, 55
	v_readlane_b32 s11, v252, 56
	s_mul_i32 s42, s13, 0x9000
	s_lshl_b32 s101, s27, 1
	s_add_i32 s42, s42, s101
	s_add_i32 s8, s8, 0x2000
	s_add_u32 s10, s10, s42
	s_addc_u32 s11, s11, 0
	s_mov_b32 m0, s8
	s_add_i32 s8, s8, 0x2000
	global_load_lds_dwordx4 v254, s[10:11]
	s_mov_b32 m0, s8
	s_add_u32 s10, s10, 0x240000
	s_addc_u32 s11, s11, 0
	global_load_lds_dwordx4 v254, s[10:11]
	s_add_i32 s98, s98, 0x8000
	s_cmp_eq_u32 s98, 0x18000
	s_cselect_b32 s98, 0x0, s98

.Lat_tile_next:
	s_add_i32 s99, s99, 0x8000
	s_cmp_eq_u32 s99, 0x18000
	s_cselect_b32 s99, 0x0, s99
	s_add_i32 s71, s71, 1
	s_add_i32 s27, s78, 4
	s_cmp_lt_u32 s71, s27
	s_cbranch_scc1 .Lat_tile_top
	s_branch .LBB0_279
